# per-lane running l (sum chains add into l, alpha applied on the rare rescale path, halves combined at loop exit); running max kept in one register across both steps
# baseline (speedup 1.0000x reference)
.LBB0_309:
	s_mov_b32 s77, s74
	s_add_u32 s4, s70, 0xffffc000
	s_mov_b32 s74, s72
	s_addc_u32 s5, s71, -1
	s_add_i32 s72, s72, s42
	s_setprio 1
	s_waitcnt lgkmcnt(4)
	v_mfma_f32_32x32x16_bf16 v[112:127], v[234:237], v[188:191], 0
	ds_read_b128 v[234:237], v233 offset:57344
	v_add_f32_e32 v1, v232, v230
	v_add_f32_e32 v1, v228, v1
	v_add_f32_e32 v1, v231, v1
	v_add_f32_e32 v1, v226, v1
	s_waitcnt lgkmcnt(4)
	v_mfma_f32_32x32x16_bf16 v[96:111], v[238:241], v[188:191], 0
	ds_read_b128 v[238:241], v254 offset:49152
	v_add_f32_e32 v1, v229, v1
	v_add_f32_e32 v1, v225, v1
	v_add_f32_e32 v1, v227, v1
	v_add_f32_e32 v1, v222, v1
	v_add_f32_e32 v1, v224, v1
	s_waitcnt lgkmcnt(4)
	v_mfma_f32_32x32x16_bf16 v[112:127], v[242:245], v[184:187], v[112:127]
	ds_read_b128 v[242:245], v254 offset:57344
	s_mov_b32 s73, m0
	s_mov_b32 m0, s72
	s_nop 0
	global_load_lds_dwordx4 v197, s[4:5]
	s_mov_b32 m0, s73
	v_add_f32_e32 v1, v220, v1
	v_add_f32_e32 v1, v223, v1
	v_exp_f32_e32 v2, v128
	v_add_f32_e32 v1, v218, v1
	s_waitcnt lgkmcnt(4)
	v_mfma_f32_32x32x16_bf16 v[96:111], v[246:249], v[184:187], v[96:111]
	ds_read_b128 v[246:249], v215 offset:49280
	v_exp_f32_e32 v12, v129
	v_add_f32_e32 v1, v221, v1
	v_exp_f32_e32 v13, v130
	v_add_f32_e32 v1, v217, v1
	s_waitcnt lgkmcnt(4)
	v_mfma_f32_32x32x16_bf16 v[112:127], v[250:253], v[180:183], v[112:127]
	ds_read_b128 v[250:253], v215 offset:57472
	v_exp_f32_e32 v14, v131
	v_add_f32_e32 v1, v219, v1
	v_exp_f32_e32 v15, v132
	s_waitcnt lgkmcnt(4)
	v_mfma_f32_32x32x16_bf16 v[96:111], v[234:237], v[180:183], v[96:111]
	ds_read_b128 v[234:237], v216 offset:49280
	s_addk_i32 s72, 0x400
	s_mov_b32 s73, m0
	s_mov_b32 m0, s72
	s_nop 0
	global_load_lds_dwordx4 v198, s[4:5]
	s_mov_b32 m0, s73
	v_add_f32_e32 v1, v2, v1
	v_exp_f32_e32 v18, v133
	v_add_f32_e32 v1, v12, v1
	s_waitcnt lgkmcnt(4)
	v_mfma_f32_32x32x16_bf16 v[112:127], v[238:241], v[176:179], v[112:127]
	ds_read_b128 v[238:241], v216 offset:57472
	v_exp_f32_e32 v19, v134
	v_add_f32_e32 v1, v13, v1
	v_exp_f32_e32 v20, v135
	v_add_f32_e32 v1, v14, v1
	s_waitcnt lgkmcnt(4)
	v_mfma_f32_32x32x16_bf16 v[96:111], v[242:245], v[176:179], v[96:111]
	ds_read_b128 v[242:245], v233 offset:49280
	v_exp_f32_e32 v21, v136
	v_add_f32_e32 v1, v15, v1
	v_exp_f32_e32 v22, v137
	s_waitcnt lgkmcnt(4)
	v_mfma_f32_32x32x16_bf16 v[112:127], v[246:249], v[172:175], v[112:127]
	ds_read_b128 v[246:249], v233 offset:57472
	s_add_i32 s4, s69, s97
	s_mov_b32 s5, m0
	s_mov_b32 m0, s4
	s_nop 0
	global_load_lds_dwordx4 v199, s[56:57]
	s_mov_b32 m0, s5
	v_add_f32_e32 v1, v18, v1
	v_exp_f32_e32 v23, v138
	v_add_f32_e32 v1, v19, v1
	v_exp_f32_e32 v24, v139
	s_waitcnt lgkmcnt(4)
	v_mfma_f32_32x32x16_bf16 v[96:111], v[250:253], v[172:175], v[96:111]
	ds_read_b128 v[250:253], v254 offset:49280
	v_add_f32_e32 v1, v20, v1
	v_exp_f32_e32 v25, v140
	v_add_f32_e32 v1, v21, v1
	s_waitcnt lgkmcnt(4)
	v_mfma_f32_32x32x16_bf16 v[112:127], v[234:237], v[168:171], v[112:127]
	ds_read_b128 v[234:237], v254 offset:57472
	v_exp_f32_e32 v26, v141
	v_add_f32_e32 v1, v22, v1
	v_exp_f32_e32 v27, v142
	v_add_f32_e32 v1, v23, v1
	s_waitcnt lgkmcnt(4)
	v_mfma_f32_32x32x16_bf16 v[96:111], v[238:241], v[168:171], v[96:111]
	s_addk_i32 s4, 0x400
	s_mov_b32 s5, m0
	s_mov_b32 m0, s4
	s_nop 0
	global_load_lds_dwordx4 v200, s[56:57]
	s_mov_b32 m0, s5
	v_exp_f32_e32 v28, v143
	v_add_f32_e32 v1, v24, v1
	v_add_f32_e32 v1, v25, v1
	v_add_f32_e32 v1, v26, v1
	s_waitcnt lgkmcnt(3)
	v_mfma_f32_32x32x16_bf16 v[112:127], v[242:245], v[164:167], v[112:127]
	v_add_f32_e32 v1, v27, v1
	v_add_f32_e32 v1, v28, v1
	v_add_f32_e32 v205, v205, v1
	v_cvt_pk_bf16_f32 v4, v230, v232
	v_cvt_pk_bf16_f32 v5, v228, v231
	s_waitcnt lgkmcnt(2)
	v_mfma_f32_32x32x16_bf16 v[96:111], v[246:249], v[164:167], v[96:111]
	v_cvt_pk_bf16_f32 v6, v226, v229
	v_cvt_pk_bf16_f32 v7, v225, v227
	v_cvt_pk_bf16_f32 v8, v222, v224
	v_cvt_pk_bf16_f32 v9, v220, v223
	s_waitcnt lgkmcnt(1)
	v_mfma_f32_32x32x16_bf16 v[112:127], v[250:253], v[160:163], v[112:127]
	v_cvt_pk_bf16_f32 v10, v218, v221
	v_cvt_pk_bf16_f32 v11, v217, v219
	v_cvt_pk_bf16_f32 v12, v2, v12
	v_cvt_pk_bf16_f32 v13, v13, v14
	v_cvt_pk_bf16_f32 v14, v15, v18
	s_waitcnt lgkmcnt(0)
	v_mfma_f32_32x32x16_bf16 v[96:111], v[234:237], v[160:163], v[96:111]
	v_cvt_pk_bf16_f32 v15, v19, v20
	v_cvt_pk_bf16_f32 v18, v21, v22
	v_cvt_pk_bf16_f32 v19, v23, v24
	v_cvt_pk_bf16_f32 v20, v25, v26
	v_cvt_pk_bf16_f32 v21, v27, v28
	s_setprio 0
	v_add_u32_e32 v2, s74, v206
	ds_read_b64_tr_b16 v[22:23], v2 offset:0
	ds_read_b64_tr_b16 v[24:25], v2 offset:0x800
	ds_read_b64_tr_b16 v[26:27], v2 offset:0x1000
	ds_read_b64_tr_b16 v[28:29], v2 offset:0x1800
	ds_read_b64_tr_b16 v[128:129], v2 offset:0x2000
	ds_read_b64_tr_b16 v[130:131], v2 offset:0x2800
	ds_read_b64_tr_b16 v[132:133], v2 offset:0x3000
	ds_read_b64_tr_b16 v[134:135], v2 offset:0x3800
	s_waitcnt lgkmcnt(6)
	s_nop 0
	v_mfma_f32_32x32x16_bf16 v[32:47], v[4:7], v[22:25], v[32:47]
	ds_read_b64_tr_b16 v[22:23], v2 offset:0x200
	ds_read_b64_tr_b16 v[24:25], v2 offset:0xa00
	s_waitcnt lgkmcnt(6)
	v_mfma_f32_32x32x16_bf16 v[32:47], v[8:11], v[26:29], v[32:47]
	ds_read_b64_tr_b16 v[26:27], v2 offset:0x1200
	ds_read_b64_tr_b16 v[28:29], v2 offset:0x1a00
	s_waitcnt lgkmcnt(6)
	v_mfma_f32_32x32x16_bf16 v[32:47], v[12:15], v[128:131], v[32:47]
	ds_read_b64_tr_b16 v[128:129], v2 offset:0x2200
	ds_read_b64_tr_b16 v[130:131], v2 offset:0x2a00
	s_waitcnt lgkmcnt(6)
	v_mfma_f32_32x32x16_bf16 v[32:47], v[18:21], v[132:135], v[32:47]
	ds_read_b64_tr_b16 v[132:133], v2 offset:0x3200
	ds_read_b64_tr_b16 v[134:135], v2 offset:0x3a00
	s_waitcnt lgkmcnt(6)
	v_mfma_f32_32x32x16_bf16 v[48:63], v[4:7], v[22:25], v[48:63]
	ds_read_b64_tr_b16 v[22:23], v2 offset:0x400
	ds_read_b64_tr_b16 v[24:25], v2 offset:0xc00
	s_waitcnt lgkmcnt(6)
	v_mfma_f32_32x32x16_bf16 v[48:63], v[8:11], v[26:29], v[48:63]
	ds_read_b64_tr_b16 v[26:27], v2 offset:0x1400
	ds_read_b64_tr_b16 v[28:29], v2 offset:0x1c00
	s_waitcnt lgkmcnt(6)
	v_mfma_f32_32x32x16_bf16 v[48:63], v[12:15], v[128:131], v[48:63]
	ds_read_b64_tr_b16 v[128:129], v2 offset:0x2400
	ds_read_b64_tr_b16 v[130:131], v2 offset:0x2c00
	s_waitcnt lgkmcnt(6)
	v_mfma_f32_32x32x16_bf16 v[48:63], v[18:21], v[132:135], v[48:63]
	ds_read_b64_tr_b16 v[132:133], v2 offset:0x3400
	ds_read_b64_tr_b16 v[134:135], v2 offset:0x3c00
	s_waitcnt lgkmcnt(6)
	v_mfma_f32_32x32x16_bf16 v[64:79], v[4:7], v[22:25], v[64:79]
	ds_read_b64_tr_b16 v[22:23], v2 offset:0x600
	ds_read_b64_tr_b16 v[24:25], v2 offset:0xe00
	v_add3_u32 v215, s69, v209, v208
	s_waitcnt lgkmcnt(6)
	v_mfma_f32_32x32x16_bf16 v[64:79], v[8:11], v[26:29], v[64:79]
	ds_read_b64_tr_b16 v[26:27], v2 offset:0x1600
	ds_read_b64_tr_b16 v[28:29], v2 offset:0x1e00
	v_add3_u32 v216, s69, v210, v208
	s_waitcnt lgkmcnt(6)
	v_mfma_f32_32x32x16_bf16 v[64:79], v[12:15], v[128:131], v[64:79]
	ds_read_b64_tr_b16 v[128:129], v2 offset:0x2600
	ds_read_b64_tr_b16 v[130:131], v2 offset:0x2e00
	v_add3_u32 v233, s69, v211, v208
	s_waitcnt lgkmcnt(6)
	v_mfma_f32_32x32x16_bf16 v[64:79], v[18:21], v[132:135], v[64:79]
	ds_read_b64_tr_b16 v[132:133], v2 offset:0x3600
	ds_read_b64_tr_b16 v[134:135], v2 offset:0x3e00
	v_add3_u32 v254, s69, v212, v208
	s_waitcnt lgkmcnt(6)
	v_mfma_f32_32x32x16_bf16 v[80:95], v[4:7], v[22:25], v[80:95]
	v_max_f32_e32 v2, v113, v112
	v_max3_f32 v2, v2, v114, v115
	v_max3_f32 v2, v2, v116, v117
	v_max3_f32 v2, v2, v118, v119
	v_max3_f32 v2, v2, v120, v121
	v_max3_f32 v2, v2, v122, v123
	v_max3_f32 v2, v2, v124, v125
	v_max3_f32 v2, v2, v126, v127
	s_waitcnt lgkmcnt(4)
	v_mfma_f32_32x32x16_bf16 v[80:95], v[8:11], v[26:29], v[80:95]
	v_max3_f32 v2, v2, v96, v97
	v_max3_f32 v2, v2, v98, v99
	v_max3_f32 v2, v2, v100, v101
	v_max3_f32 v2, v2, v102, v103
	v_max3_f32 v2, v2, v104, v105
	v_max3_f32 v2, v2, v106, v107
	v_max3_f32 v2, v2, v108, v109
	v_max3_f32 v2, v2, v110, v111
	s_waitcnt lgkmcnt(2)
	v_mfma_f32_32x32x16_bf16 v[80:95], v[12:15], v[128:131], v[80:95]
	v_sub_f32_e32 v4, v2, v214
	v_cmp_ge_f32_e32 vcc, 0x42b504f3, v4
	s_waitcnt lgkmcnt(0)
	v_mfma_f32_32x32x16_bf16 v[80:95], v[18:21], v[132:135], v[80:95]
	s_cmp_eq_u64 vcc, exec
	s_cbranch_scc0 .Lattn0_slowA
.Lattn0_backA:
	s_waitcnt vmcnt(4) lgkmcnt(0)
	s_barrier
	ds_read_b128 v[234:237], v215 offset:49152
	ds_read_b128 v[238:241], v215 offset:57344
	ds_read_b128 v[242:245], v216 offset:49152
	ds_read_b128 v[246:249], v216 offset:57344
	ds_read_b128 v[250:253], v233 offset:49152
	v_mul_f32_e32 v5, 0xbe0293ee, v214
	v_fmamk_f32 v6, v112, 0x3e0293ee, v5
	v_fmamk_f32 v7, v113, 0x3e0293ee, v5
	v_fmamk_f32 v8, v114, 0x3e0293ee, v5
	v_fmamk_f32 v9, v115, 0x3e0293ee, v5
	v_fmamk_f32 v10, v116, 0x3e0293ee, v5
	v_fmamk_f32 v11, v117, 0x3e0293ee, v5
	v_fmamk_f32 v12, v118, 0x3e0293ee, v5
	v_fmamk_f32 v13, v119, 0x3e0293ee, v5
	v_fmamk_f32 v14, v120, 0x3e0293ee, v5
	v_fmamk_f32 v15, v121, 0x3e0293ee, v5
	v_fmamk_f32 v18, v122, 0x3e0293ee, v5
	v_fmamk_f32 v19, v123, 0x3e0293ee, v5
	v_fmamk_f32 v20, v124, 0x3e0293ee, v5
	v_fmamk_f32 v21, v125, 0x3e0293ee, v5
	v_fmamk_f32 v22, v126, 0x3e0293ee, v5
	v_fmamk_f32 v23, v127, 0x3e0293ee, v5
	v_fmamk_f32 v24, v96, 0x3e0293ee, v5
	v_fmamk_f32 v25, v97, 0x3e0293ee, v5
	v_fmamk_f32 v26, v98, 0x3e0293ee, v5
	v_fmamk_f32 v27, v99, 0x3e0293ee, v5
	v_fmamk_f32 v28, v100, 0x3e0293ee, v5
	v_fmamk_f32 v29, v101, 0x3e0293ee, v5
	v_fmamk_f32 v30, v102, 0x3e0293ee, v5
	v_fmamk_f32 v31, v103, 0x3e0293ee, v5
	v_fmamk_f32 v128, v104, 0x3e0293ee, v5
	v_fmamk_f32 v129, v105, 0x3e0293ee, v5
	v_fmamk_f32 v130, v106, 0x3e0293ee, v5
	v_fmamk_f32 v131, v107, 0x3e0293ee, v5
	v_fmamk_f32 v132, v108, 0x3e0293ee, v5
	v_fmamk_f32 v133, v109, 0x3e0293ee, v5
	v_fmamk_f32 v134, v110, 0x3e0293ee, v5
	v_fmac_f32_e32 v5, 0x3e0293ee, v111
	s_setprio 1
	s_waitcnt lgkmcnt(4)
	v_mfma_f32_32x32x16_bf16 v[112:127], v[234:237], v[188:191], 0
	ds_read_b128 v[234:237], v233 offset:57344
	v_exp_f32_e32 v135, v6
	v_exp_f32_e32 v136, v7
	v_exp_f32_e32 v137, v8
	v_exp_f32_e32 v138, v9
	s_waitcnt lgkmcnt(4)
	v_mfma_f32_32x32x16_bf16 v[96:111], v[238:241], v[188:191], 0
	ds_read_b128 v[238:241], v254 offset:49152
	v_exp_f32_e32 v10, v10
	v_exp_f32_e32 v11, v11
	v_exp_f32_e32 v12, v12
	s_waitcnt lgkmcnt(4)
	v_mfma_f32_32x32x16_bf16 v[112:127], v[242:245], v[184:187], v[112:127]
	ds_read_b128 v[242:245], v254 offset:57344
	s_add_i32 s4, s77, s42
	s_mov_b32 s5, m0
	s_mov_b32 m0, s4
	s_nop 0
	global_load_lds_dwordx4 v197, s[70:71]
	s_mov_b32 m0, s5
	v_exp_f32_e32 v13, v13
	v_exp_f32_e32 v14, v14
	v_exp_f32_e32 v15, v15
	v_exp_f32_e32 v18, v18
	s_waitcnt lgkmcnt(4)
	v_mfma_f32_32x32x16_bf16 v[96:111], v[246:249], v[184:187], v[96:111]
	ds_read_b128 v[246:249], v215 offset:49280
	v_exp_f32_e32 v19, v19
	v_exp_f32_e32 v20, v20
	v_exp_f32_e32 v21, v21
	s_waitcnt lgkmcnt(4)
	v_mfma_f32_32x32x16_bf16 v[112:127], v[250:253], v[180:183], v[112:127]
	ds_read_b128 v[250:253], v215 offset:57472
	v_exp_f32_e32 v22, v22
	v_exp_f32_e32 v23, v23
	v_exp_f32_e32 v7, v24
	v_exp_f32_e32 v24, v25
	s_waitcnt lgkmcnt(4)
	v_mfma_f32_32x32x16_bf16 v[96:111], v[234:237], v[180:183], v[96:111]
	ds_read_b128 v[234:237], v216 offset:49280
	s_addk_i32 s4, 0x400
	s_mov_b32 s5, m0
	s_mov_b32 m0, s4
	s_nop 0
	global_load_lds_dwordx4 v198, s[70:71]
	s_mov_b32 m0, s5
	v_exp_f32_e32 v25, v26
	v_exp_f32_e32 v26, v27
	v_exp_f32_e32 v27, v28
	s_waitcnt lgkmcnt(4)
	v_mfma_f32_32x32x16_bf16 v[112:127], v[238:241], v[176:179], v[112:127]
	ds_read_b128 v[238:241], v216 offset:57472
	v_exp_f32_e32 v28, v29
	v_exp_f32_e32 v29, v30
	v_exp_f32_e32 v30, v31
	v_exp_f32_e32 v31, v128
	s_waitcnt lgkmcnt(4)
	v_mfma_f32_32x32x16_bf16 v[96:111], v[242:245], v[176:179], v[96:111]
	ds_read_b128 v[242:245], v233 offset:49280
	v_exp_f32_e32 v128, v129
	v_exp_f32_e32 v129, v130
	v_exp_f32_e32 v130, v131
	v_exp_f32_e32 v131, v132
	s_waitcnt lgkmcnt(4)
	v_mfma_f32_32x32x16_bf16 v[112:127], v[246:249], v[172:175], v[112:127]
	ds_read_b128 v[246:249], v233 offset:57472
	s_add_u32 s4, s56, 0x4000
	s_addc_u32 s5, s57, 0
	s_add_i32 s72, s74, s97
	s_mov_b32 s73, m0
	s_mov_b32 m0, s72
	s_nop 0
	global_load_lds_dwordx4 v199, s[4:5]
	s_mov_b32 m0, s73
	v_exp_f32_e32 v132, v133
	v_exp_f32_e32 v133, v134
	v_exp_f32_e32 v134, v5
	s_waitcnt lgkmcnt(4)
	v_mfma_f32_32x32x16_bf16 v[96:111], v[250:253], v[172:175], v[96:111]
	ds_read_b128 v[250:253], v254 offset:49280
	v_add_f32_e32 v5, v136, v135
	v_add_f32_e32 v5, v137, v5
	v_add_f32_e32 v5, v138, v5
	v_add_f32_e32 v5, v10, v5
	v_add_f32_e32 v5, v11, v5
	v_add_f32_e32 v5, v12, v5
	v_add_f32_e32 v5, v13, v5
	s_waitcnt lgkmcnt(4)
	v_mfma_f32_32x32x16_bf16 v[112:127], v[234:237], v[168:171], v[112:127]
	ds_read_b128 v[234:237], v254 offset:57472
	v_add_f32_e32 v5, v14, v5
	v_add_f32_e32 v5, v15, v5
	v_add_f32_e32 v5, v18, v5
	v_add_f32_e32 v5, v19, v5
	v_add_f32_e32 v5, v20, v5
	v_add_f32_e32 v5, v21, v5
	v_add_f32_e32 v5, v22, v5
	s_waitcnt lgkmcnt(4)
	v_mfma_f32_32x32x16_bf16 v[96:111], v[238:241], v[168:171], v[96:111]
	s_addk_i32 s72, 0x400
	s_mov_b32 s73, m0
	s_mov_b32 m0, s72
	s_nop 0
	global_load_lds_dwordx4 v200, s[4:5]
	s_mov_b32 m0, s73
	v_add_f32_e32 v5, v23, v5
	v_add_f32_e32 v5, v7, v5
	v_add_f32_e32 v5, v24, v5
	v_add_f32_e32 v5, v25, v5
	v_add_f32_e32 v5, v26, v5
	v_add_f32_e32 v5, v27, v5
	v_add_f32_e32 v5, v28, v5
	s_waitcnt lgkmcnt(3)
	v_mfma_f32_32x32x16_bf16 v[112:127], v[242:245], v[164:167], v[112:127]
	v_add_f32_e32 v5, v29, v5
	v_add_f32_e32 v5, v30, v5
	v_add_f32_e32 v5, v31, v5
	v_add_f32_e32 v5, v128, v5
	v_add_f32_e32 v5, v129, v5
	v_add_f32_e32 v5, v130, v5
	v_add_f32_e32 v5, v131, v5
	s_waitcnt lgkmcnt(2)
	v_mfma_f32_32x32x16_bf16 v[96:111], v[246:249], v[164:167], v[96:111]
	v_add_f32_e32 v5, v132, v5
	v_add_f32_e32 v5, v133, v5
	v_add_f32_e32 v5, v134, v5
	v_add_f32_e32 v205, v205, v5
	v_cvt_pk_bf16_f32 v8, v135, v136
	v_cvt_pk_bf16_f32 v9, v137, v138
	v_cvt_pk_bf16_f32 v10, v10, v11
	s_waitcnt lgkmcnt(1)
	v_mfma_f32_32x32x16_bf16 v[112:127], v[250:253], v[160:163], v[112:127]
	v_cvt_pk_bf16_f32 v11, v12, v13
	v_cvt_pk_bf16_f32 v12, v14, v15
	v_cvt_pk_bf16_f32 v13, v18, v19
	v_cvt_pk_bf16_f32 v14, v20, v21
	v_cvt_pk_bf16_f32 v15, v22, v23
	v_cvt_pk_bf16_f32 v18, v7, v24
	s_waitcnt lgkmcnt(0)
	v_mfma_f32_32x32x16_bf16 v[96:111], v[234:237], v[160:163], v[96:111]
	v_cvt_pk_bf16_f32 v19, v25, v26
	v_cvt_pk_bf16_f32 v20, v27, v28
	v_cvt_pk_bf16_f32 v21, v29, v30
	v_cvt_pk_bf16_f32 v22, v31, v128
	v_cvt_pk_bf16_f32 v23, v129, v130
	v_cvt_pk_bf16_f32 v24, v131, v132
	v_cvt_pk_bf16_f32 v25, v133, v134
	s_setprio 0
	v_add_u32_e32 v7, s77, v206
	ds_read_b64_tr_b16 v[26:27], v7 offset:0
	ds_read_b64_tr_b16 v[28:29], v7 offset:0x800
	ds_read_b64_tr_b16 v[128:129], v7 offset:0x1000
	ds_read_b64_tr_b16 v[130:131], v7 offset:0x1800
	ds_read_b64_tr_b16 v[132:133], v7 offset:0x2000
	ds_read_b64_tr_b16 v[134:135], v7 offset:0x2800
	ds_read_b64_tr_b16 v[136:137], v7 offset:0x3000
	ds_read_b64_tr_b16 v[138:139], v7 offset:0x3800
	s_waitcnt lgkmcnt(6)
	s_nop 0
	v_mfma_f32_32x32x16_bf16 v[32:47], v[8:11], v[26:29], v[32:47]
	ds_read_b64_tr_b16 v[26:27], v7 offset:0x200
	ds_read_b64_tr_b16 v[28:29], v7 offset:0xa00
	s_waitcnt lgkmcnt(6)
	v_mfma_f32_32x32x16_bf16 v[32:47], v[12:15], v[128:131], v[32:47]
	ds_read_b64_tr_b16 v[128:129], v7 offset:0x1200
	ds_read_b64_tr_b16 v[130:131], v7 offset:0x1a00
	v_mul_f32_e32 v140, 0xbe0293ee, v214
	v_fmamk_f32 v230, v112, 0x3e0293ee, v140
	v_fmamk_f32 v232, v113, 0x3e0293ee, v140
	s_waitcnt lgkmcnt(6)
	v_mfma_f32_32x32x16_bf16 v[32:47], v[18:21], v[132:135], v[32:47]
	ds_read_b64_tr_b16 v[132:133], v7 offset:0x2200
	ds_read_b64_tr_b16 v[134:135], v7 offset:0x2a00
	v_exp_f32_e32 v230, v230
	v_exp_f32_e32 v232, v232
	v_fmamk_f32 v228, v114, 0x3e0293ee, v140
	v_fmamk_f32 v231, v115, 0x3e0293ee, v140
	s_waitcnt lgkmcnt(6)
	v_mfma_f32_32x32x16_bf16 v[32:47], v[22:25], v[136:139], v[32:47]
	ds_read_b64_tr_b16 v[136:137], v7 offset:0x3200
	ds_read_b64_tr_b16 v[138:139], v7 offset:0x3a00
	v_exp_f32_e32 v228, v228
	v_exp_f32_e32 v231, v231
	v_fmamk_f32 v226, v116, 0x3e0293ee, v140
	v_fmamk_f32 v229, v117, 0x3e0293ee, v140
	s_waitcnt lgkmcnt(6)
	v_mfma_f32_32x32x16_bf16 v[48:63], v[8:11], v[26:29], v[48:63]
	ds_read_b64_tr_b16 v[26:27], v7 offset:0x400
	ds_read_b64_tr_b16 v[28:29], v7 offset:0xc00
	v_exp_f32_e32 v226, v226
	v_exp_f32_e32 v229, v229
	v_fmamk_f32 v225, v118, 0x3e0293ee, v140
	v_fmamk_f32 v227, v119, 0x3e0293ee, v140
	s_waitcnt lgkmcnt(6)
	v_mfma_f32_32x32x16_bf16 v[48:63], v[12:15], v[128:131], v[48:63]
	ds_read_b64_tr_b16 v[128:129], v7 offset:0x1400
	ds_read_b64_tr_b16 v[130:131], v7 offset:0x1c00
	v_exp_f32_e32 v225, v225
	v_exp_f32_e32 v227, v227
	v_fmamk_f32 v222, v120, 0x3e0293ee, v140
	v_fmamk_f32 v224, v121, 0x3e0293ee, v140
	s_waitcnt lgkmcnt(6)
	v_mfma_f32_32x32x16_bf16 v[48:63], v[18:21], v[132:135], v[48:63]
	ds_read_b64_tr_b16 v[132:133], v7 offset:0x2400
	ds_read_b64_tr_b16 v[134:135], v7 offset:0x2c00
	v_exp_f32_e32 v222, v222
	v_exp_f32_e32 v224, v224
	v_fmamk_f32 v220, v122, 0x3e0293ee, v140
	v_fmamk_f32 v223, v123, 0x3e0293ee, v140
	s_waitcnt lgkmcnt(6)
	v_mfma_f32_32x32x16_bf16 v[48:63], v[22:25], v[136:139], v[48:63]
	ds_read_b64_tr_b16 v[136:137], v7 offset:0x3400
	ds_read_b64_tr_b16 v[138:139], v7 offset:0x3c00
	v_exp_f32_e32 v220, v220
	v_exp_f32_e32 v223, v223
	v_fmamk_f32 v218, v124, 0x3e0293ee, v140
	v_fmamk_f32 v221, v125, 0x3e0293ee, v140
	s_waitcnt lgkmcnt(6)
	v_mfma_f32_32x32x16_bf16 v[64:79], v[8:11], v[26:29], v[64:79]
	ds_read_b64_tr_b16 v[26:27], v7 offset:0x600
	ds_read_b64_tr_b16 v[28:29], v7 offset:0xe00
	v_exp_f32_e32 v218, v218
	v_exp_f32_e32 v221, v221
	v_fmamk_f32 v217, v126, 0x3e0293ee, v140
	v_fmamk_f32 v219, v127, 0x3e0293ee, v140
	s_waitcnt lgkmcnt(6)
	v_mfma_f32_32x32x16_bf16 v[64:79], v[12:15], v[128:131], v[64:79]
	ds_read_b64_tr_b16 v[128:129], v7 offset:0x1600
	ds_read_b64_tr_b16 v[130:131], v7 offset:0x1e00
	v_exp_f32_e32 v217, v217
	v_exp_f32_e32 v219, v219
	s_waitcnt lgkmcnt(6)
	v_mfma_f32_32x32x16_bf16 v[64:79], v[18:21], v[132:135], v[64:79]
	ds_read_b64_tr_b16 v[132:133], v7 offset:0x2600
	ds_read_b64_tr_b16 v[134:135], v7 offset:0x2e00
	v_add3_u32 v215, s74, v209, v208
	v_add3_u32 v216, s74, v210, v208
	s_waitcnt lgkmcnt(6)
	v_mfma_f32_32x32x16_bf16 v[64:79], v[22:25], v[136:139], v[64:79]
	ds_read_b64_tr_b16 v[136:137], v7 offset:0x3600
	ds_read_b64_tr_b16 v[138:139], v7 offset:0x3e00
	v_add3_u32 v233, s74, v211, v208
	v_add3_u32 v254, s74, v212, v208
	s_waitcnt lgkmcnt(6)
	v_mfma_f32_32x32x16_bf16 v[80:95], v[8:11], v[26:29], v[80:95]
	v_max_f32_e32 v7, v113, v112
	v_max3_f32 v7, v7, v114, v115
	v_max3_f32 v7, v7, v116, v117
	v_max3_f32 v7, v7, v118, v119
	v_max3_f32 v7, v7, v120, v121
	v_max3_f32 v7, v7, v122, v123
	v_max3_f32 v7, v7, v124, v125
	v_max3_f32 v7, v7, v126, v127
	s_waitcnt lgkmcnt(4)
	v_mfma_f32_32x32x16_bf16 v[80:95], v[12:15], v[128:131], v[80:95]
	v_max3_f32 v7, v7, v96, v97
	v_max3_f32 v7, v7, v98, v99
	v_max3_f32 v7, v7, v100, v101
	v_max3_f32 v7, v7, v102, v103
	v_max3_f32 v7, v7, v104, v105
	v_max3_f32 v7, v7, v106, v107
	v_max3_f32 v7, v7, v108, v109
	v_max3_f32 v7, v7, v110, v111
	s_waitcnt lgkmcnt(2)
	v_mfma_f32_32x32x16_bf16 v[80:95], v[18:21], v[132:135], v[80:95]
	v_sub_f32_e32 v8, v7, v214
	v_cmp_ge_f32_e32 vcc, 0x42b504f3, v8
	s_waitcnt lgkmcnt(0)
	v_mfma_f32_32x32x16_bf16 v[80:95], v[22:25], v[136:139], v[80:95]
	s_cmp_eq_u64 vcc, exec
	s_cbranch_scc0 .Lattn0_slowB
.Lattn0_backB:
	v_mul_f32_e32 v2, 0xbe0293ee, v214
	s_add_u32 s56, s56, 0x8000
	s_addc_u32 s57, s57, 0
	s_add_i32 s4, s45, 2
	s_add_u32 s70, s70, 0x8000
	s_addc_u32 s71, s71, 0
	s_waitcnt vmcnt(4) lgkmcnt(0)
	s_barrier
	ds_read_b128 v[234:237], v215 offset:49152
	ds_read_b128 v[238:241], v215 offset:57344
	ds_read_b128 v[242:245], v216 offset:49152
	ds_read_b128 v[246:249], v216 offset:57344
	ds_read_b128 v[250:253], v233 offset:49152
	v_pk_fma_f32 v[142:143], v[110:111], s[12:13], v[2:3] op_sel_hi:[1,0,0]
	v_pk_fma_f32 v[140:141], v[108:109], s[12:13], v[2:3] op_sel_hi:[1,0,0]
	v_pk_fma_f32 v[138:139], v[106:107], s[12:13], v[2:3] op_sel_hi:[1,0,0]
	v_pk_fma_f32 v[136:137], v[104:105], s[12:13], v[2:3] op_sel_hi:[1,0,0]
	v_pk_fma_f32 v[134:135], v[102:103], s[12:13], v[2:3] op_sel_hi:[1,0,0]
	v_pk_fma_f32 v[132:133], v[100:101], s[12:13], v[2:3] op_sel_hi:[1,0,0]
	v_pk_fma_f32 v[130:131], v[98:99], s[12:13], v[2:3] op_sel_hi:[1,0,0]
	v_pk_fma_f32 v[128:129], v[96:97], s[12:13], v[2:3] op_sel_hi:[1,0,0]
	s_cmp_ge_i32 s4, s21
	s_cbranch_scc1 .Lattn0_exitB
	s_mov_b32 s45, s4
	s_mov_b32 s72, s69
	s_mov_b32 s69, s77
	s_branch .LBB0_309
.Lattn0_exitB:
	s_waitcnt lgkmcnt(0)
	v_mov_b32_e32 v6, v205
	v_mov_b32_e32 v7, 1.0
	s_nop 0
	v_permlane32_swap_b32_e32 v205, v6
	v_add_f32_e32 v205, v205, v6
	s_branch .LBB0_321
.Lattn0_slowA:
	v_mov_b32_e32 v4, v2
	s_nop 1
	v_permlane32_swap_b32_e32 v2, v4
	v_max_f32_e32 v2, v4, v2
	v_max_f32_e32 v2, v214, v2
	v_sub_f32_e32 v4, v214, v2
	v_mul_f32_e32 v4, 0x3e0293ee, v4
	v_exp_f32_e32 v4, v4
	s_nop 0
	v_cmp_gt_f32_e32 vcc, 1.0, v4
	v_mul_f32_e32 v205, v205, v4
	v_mov_b32_e32 v214, v2
	s_cbranch_vccz .Lattn0_backA
	s_and_saveexec_b64 s[72:73], s[2:3]
	ds_write_b32 v204, v4 offset:128
	s_or_b64 exec, exec, s[72:73]
	s_waitcnt lgkmcnt(0)
	ds_read_b128 v[6:9], v203 offset:224
	ds_read_b128 v[10:13], v203 offset:192
	ds_read_b128 v[18:21], v203 offset:160
	ds_read_b128 v[22:25], v203 offset:128
	s_waitcnt lgkmcnt(3)
	v_pk_mul_f32 v[46:47], v[46:47], v[8:9]
	s_waitcnt lgkmcnt(2)
	v_pk_mul_f32 v[42:43], v[42:43], v[12:13]
	s_waitcnt lgkmcnt(1)
	v_pk_mul_f32 v[38:39], v[38:39], v[20:21]
	s_waitcnt lgkmcnt(0)
	v_pk_mul_f32 v[34:35], v[34:35], v[24:25]
	v_pk_mul_f32 v[44:45], v[44:45], v[6:7]
	v_pk_mul_f32 v[40:41], v[40:41], v[10:11]
	v_pk_mul_f32 v[36:37], v[36:37], v[18:19]
	v_pk_mul_f32 v[32:33], v[32:33], v[22:23]
	v_pk_mul_f32 v[62:63], v[62:63], v[8:9]
	v_pk_mul_f32 v[58:59], v[58:59], v[12:13]
	v_pk_mul_f32 v[54:55], v[54:55], v[20:21]
	v_pk_mul_f32 v[50:51], v[50:51], v[24:25]
	v_pk_mul_f32 v[60:61], v[60:61], v[6:7]
	v_pk_mul_f32 v[56:57], v[56:57], v[10:11]
	v_pk_mul_f32 v[52:53], v[52:53], v[18:19]
	v_pk_mul_f32 v[48:49], v[48:49], v[22:23]
	v_pk_mul_f32 v[78:79], v[78:79], v[8:9]
	v_pk_mul_f32 v[74:75], v[74:75], v[12:13]
	v_pk_mul_f32 v[70:71], v[70:71], v[20:21]
	v_pk_mul_f32 v[66:67], v[66:67], v[24:25]
	v_pk_mul_f32 v[76:77], v[76:77], v[6:7]
	v_pk_mul_f32 v[72:73], v[72:73], v[10:11]
	v_pk_mul_f32 v[68:69], v[68:69], v[18:19]
	v_pk_mul_f32 v[64:65], v[64:65], v[22:23]
	v_pk_mul_f32 v[94:95], v[94:95], v[8:9]
	v_pk_mul_f32 v[90:91], v[90:91], v[12:13]
	v_pk_mul_f32 v[86:87], v[86:87], v[20:21]
	v_pk_mul_f32 v[82:83], v[82:83], v[24:25]
	v_pk_mul_f32 v[92:93], v[92:93], v[6:7]
	v_pk_mul_f32 v[88:89], v[88:89], v[10:11]
	v_pk_mul_f32 v[84:85], v[84:85], v[18:19]
	v_pk_mul_f32 v[80:81], v[80:81], v[22:23]
	s_branch .Lattn0_backA
.Lattn0_slowB:
	v_mov_b32_e32 v8, v7
	s_nop 1
	v_permlane32_swap_b32_e32 v7, v8
	v_max_f32_e32 v7, v8, v7
	v_max_f32_e32 v8, v214, v7
	v_sub_f32_e32 v7, v214, v8
	v_mul_f32_e32 v7, 0x3e0293ee, v7
	v_exp_f32_e32 v7, v7
	v_mov_b32_e32 v214, v8
	v_cmp_gt_f32_e32 vcc, 1.0, v7
	v_mul_f32_e32 v205, v205, v7
	s_cbranch_vccz .Lattn0_recompB
	s_and_saveexec_b64 s[72:73], s[2:3]
	ds_write_b32 v204, v7 offset:128
	s_or_b64 exec, exec, s[72:73]
	s_waitcnt lgkmcnt(0)
	ds_read_b128 v[10:13], v203 offset:224
	ds_read_b128 v[18:21], v203 offset:192
	ds_read_b128 v[22:25], v203 offset:160
	ds_read_b128 v[26:29], v203 offset:128
	s_waitcnt lgkmcnt(3)
	v_pk_mul_f32 v[46:47], v[46:47], v[12:13]
	s_waitcnt lgkmcnt(2)
	v_pk_mul_f32 v[42:43], v[42:43], v[20:21]
	s_waitcnt lgkmcnt(1)
	v_pk_mul_f32 v[38:39], v[38:39], v[24:25]
	s_waitcnt lgkmcnt(0)
	v_pk_mul_f32 v[34:35], v[34:35], v[28:29]
	v_pk_mul_f32 v[44:45], v[44:45], v[10:11]
	v_pk_mul_f32 v[40:41], v[40:41], v[18:19]
	v_pk_mul_f32 v[36:37], v[36:37], v[22:23]
	v_pk_mul_f32 v[32:33], v[32:33], v[26:27]
	v_pk_mul_f32 v[62:63], v[62:63], v[12:13]
	v_pk_mul_f32 v[58:59], v[58:59], v[20:21]
	v_pk_mul_f32 v[54:55], v[54:55], v[24:25]
	v_pk_mul_f32 v[50:51], v[50:51], v[28:29]
	v_pk_mul_f32 v[60:61], v[60:61], v[10:11]
	v_pk_mul_f32 v[56:57], v[56:57], v[18:19]
	v_pk_mul_f32 v[52:53], v[52:53], v[22:23]
	v_pk_mul_f32 v[48:49], v[48:49], v[26:27]
	v_pk_mul_f32 v[78:79], v[78:79], v[12:13]
	v_pk_mul_f32 v[74:75], v[74:75], v[20:21]
	v_pk_mul_f32 v[70:71], v[70:71], v[24:25]
	v_pk_mul_f32 v[66:67], v[66:67], v[28:29]
	v_pk_mul_f32 v[76:77], v[76:77], v[10:11]
	v_pk_mul_f32 v[72:73], v[72:73], v[18:19]
	v_pk_mul_f32 v[68:69], v[68:69], v[22:23]
	v_pk_mul_f32 v[64:65], v[64:65], v[26:27]
	v_pk_mul_f32 v[94:95], v[94:95], v[12:13]
	v_pk_mul_f32 v[90:91], v[90:91], v[20:21]
	v_pk_mul_f32 v[86:87], v[86:87], v[24:25]
	v_pk_mul_f32 v[82:83], v[82:83], v[28:29]
	v_pk_mul_f32 v[92:93], v[92:93], v[10:11]
	v_pk_mul_f32 v[88:89], v[88:89], v[18:19]
	v_pk_mul_f32 v[84:85], v[84:85], v[22:23]
	v_pk_mul_f32 v[80:81], v[80:81], v[26:27]
